# in_proj output stores write-through (sc1): the grid barrier after in_proj no longer has a large dirty set to write back
# baseline (speedup 1.0000x reference)
.Lie0_go:
	s_lshl_b32 s2, s2, 1
	s_lshl_b32 s54, s42, 4
	s_mov_b32 s55, 0
	s_mul_i32 s64, s42, 80
	s_mov_b32 s65, 0
	v_mad_u64_u32 v[134:135], vcc, v132, s42, 0
	v_add_u32_e32 v64, s2, v130
	s_nop 0
	v_lshl_add_u64 v[134:135], s[40:41], 0, v[134:135]
	v_lshl_add_u64 v[134:135], v[64:65], 0, v[134:135]
	v_cvt_pk_bf16_f32 v126, v126, v127
	v_cvt_pk_bf16_f32 v127, v128, v129
	v_cvt_pk_bf16_f32 v128, v122, v123
	v_cvt_pk_bf16_f32 v129, v124, v125
	global_store_dwordx4 v[134:135], v[126:129], off sc1
	v_lshl_add_u64 v[134:135], s[54:55], 0, v[134:135]
	v_cvt_pk_bf16_f32 v110, v110, v111
	v_cvt_pk_bf16_f32 v111, v112, v113
	v_cvt_pk_bf16_f32 v112, v106, v107
	v_cvt_pk_bf16_f32 v113, v108, v109
	global_store_dwordx4 v[134:135], v[110:113], off sc1
	v_lshl_add_u64 v[134:135], s[54:55], 0, v[134:135]
	v_cvt_pk_bf16_f32 v94, v94, v95
	v_cvt_pk_bf16_f32 v95, v96, v97
	v_cvt_pk_bf16_f32 v96, v90, v91
	v_cvt_pk_bf16_f32 v97, v92, v93
	global_store_dwordx4 v[134:135], v[94:97], off sc1
	v_lshl_add_u64 v[134:135], s[54:55], 0, v[134:135]
	v_cvt_pk_bf16_f32 v78, v78, v79
	v_cvt_pk_bf16_f32 v79, v80, v81
	v_cvt_pk_bf16_f32 v80, v74, v75
	v_cvt_pk_bf16_f32 v81, v76, v77
	global_store_dwordx4 v[134:135], v[78:81], off sc1
	v_lshl_add_u64 v[134:135], s[64:65], 0, v[134:135]
	v_cvt_pk_bf16_f32 v60, v60, v61
	v_cvt_pk_bf16_f32 v61, v62, v63
	v_cvt_pk_bf16_f32 v62, v56, v57
	v_cvt_pk_bf16_f32 v63, v58, v59
	global_store_dwordx4 v[134:135], v[60:63], off sc1
	v_lshl_add_u64 v[134:135], s[54:55], 0, v[134:135]
	v_cvt_pk_bf16_f32 v44, v44, v45
	v_cvt_pk_bf16_f32 v45, v46, v47
	v_cvt_pk_bf16_f32 v46, v40, v41
	v_cvt_pk_bf16_f32 v47, v42, v43
	global_store_dwordx4 v[134:135], v[44:47], off sc1
	v_lshl_add_u64 v[134:135], s[54:55], 0, v[134:135]
	v_cvt_pk_bf16_f32 v28, v28, v29
	v_cvt_pk_bf16_f32 v29, v30, v31
	v_cvt_pk_bf16_f32 v30, v24, v25
	v_cvt_pk_bf16_f32 v31, v26, v27
	global_store_dwordx4 v[134:135], v[28:31], off sc1
	v_lshl_add_u64 v[134:135], s[54:55], 0, v[134:135]
	v_cvt_pk_bf16_f32 v12, v12, v13
	v_cvt_pk_bf16_f32 v13, v14, v15
	v_cvt_pk_bf16_f32 v14, v8, v9
	v_cvt_pk_bf16_f32 v15, v10, v11
	global_store_dwordx4 v[134:135], v[12:15], off sc1

.Lie1_go:
	s_lshl_b32 s2, s2, 1
	s_lshl_b32 s54, s42, 4
	s_mov_b32 s55, 0
	s_mul_i32 s64, s42, 80
	s_mov_b32 s65, 0
	v_mad_u64_u32 v[134:135], vcc, v132, s42, 0
	v_add_u32_e32 v64, s2, v130
	s_nop 0
	v_lshl_add_u64 v[134:135], s[40:41], 0, v[134:135]
	v_lshl_add_u64 v[134:135], v[64:65], 0, v[134:135]
	v_cvt_pk_bf16_f32 v118, v118, v119
	v_cvt_pk_bf16_f32 v119, v120, v121
	v_cvt_pk_bf16_f32 v120, v114, v115
	v_cvt_pk_bf16_f32 v121, v116, v117
	global_store_dwordx4 v[134:135], v[118:121], off sc1
	v_lshl_add_u64 v[134:135], s[54:55], 0, v[134:135]
	v_cvt_pk_bf16_f32 v102, v102, v103
	v_cvt_pk_bf16_f32 v103, v104, v105
	v_cvt_pk_bf16_f32 v104, v98, v99
	v_cvt_pk_bf16_f32 v105, v100, v101
	global_store_dwordx4 v[134:135], v[102:105], off sc1
	v_lshl_add_u64 v[134:135], s[54:55], 0, v[134:135]
	v_cvt_pk_bf16_f32 v86, v86, v87
	v_cvt_pk_bf16_f32 v87, v88, v89
	v_cvt_pk_bf16_f32 v88, v82, v83
	v_cvt_pk_bf16_f32 v89, v84, v85
	global_store_dwordx4 v[134:135], v[86:89], off sc1
	v_lshl_add_u64 v[134:135], s[54:55], 0, v[134:135]
	v_cvt_pk_bf16_f32 v70, v70, v71
	v_cvt_pk_bf16_f32 v71, v72, v73
	v_cvt_pk_bf16_f32 v72, v66, v67
	v_cvt_pk_bf16_f32 v73, v68, v69
	global_store_dwordx4 v[134:135], v[70:73], off sc1
	v_lshl_add_u64 v[134:135], s[64:65], 0, v[134:135]
	v_cvt_pk_bf16_f32 v52, v52, v53
	v_cvt_pk_bf16_f32 v53, v54, v55
	v_cvt_pk_bf16_f32 v54, v48, v49
	v_cvt_pk_bf16_f32 v55, v50, v51
	global_store_dwordx4 v[134:135], v[52:55], off sc1
	v_lshl_add_u64 v[134:135], s[54:55], 0, v[134:135]
	v_cvt_pk_bf16_f32 v36, v36, v37
	v_cvt_pk_bf16_f32 v37, v38, v39
	v_cvt_pk_bf16_f32 v38, v32, v33
	v_cvt_pk_bf16_f32 v39, v34, v35
	global_store_dwordx4 v[134:135], v[36:39], off sc1
	v_lshl_add_u64 v[134:135], s[54:55], 0, v[134:135]
	v_cvt_pk_bf16_f32 v20, v20, v21
	v_cvt_pk_bf16_f32 v21, v22, v23
	v_cvt_pk_bf16_f32 v22, v16, v17
	v_cvt_pk_bf16_f32 v23, v18, v19
	global_store_dwordx4 v[134:135], v[20:23], off sc1
	v_lshl_add_u64 v[134:135], s[54:55], 0, v[134:135]
	v_cvt_pk_bf16_f32 v4, v4, v5
	v_cvt_pk_bf16_f32 v5, v6, v7
	v_cvt_pk_bf16_f32 v6, v0, v1
	v_cvt_pk_bf16_f32 v7, v2, v3
	global_store_dwordx4 v[134:135], v[4:7], off sc1
